# ff1 epilogue: store data+addresses exchanged across lanes with ds_bpermute so four consecutive lanes write one row's contiguous 64 bytes
# speedup vs baseline: 1.0036x; 1.0036x over previous
; #define GAS __attribute__((address_space(1)))
; DI unsigned pk2(float lo, float hi) { f32x2 v = {lo, hi}; bf16x2_t b = __builtin_convertvector(v, bf16x2_t); return __builtin_bit_cast(unsigned, b); }
;     __device__ __forceinline__ void operator()(const f32x4 (&acc)[2][2][4][2], const Unit& u, int wr, int wc, int fr, int fq) const {
;         const int row0 = u.pm * BM + wr * 64 + fr;
; #pragma unroll
;         for (int ai = 0; ai < 2; ++ai)
; #pragma unroll
;             for (int m = 0; m < 4; ++m) { const int row = row0 + ai * HALF + m * 16;
; #pragma unroll
;                 for (int bj = 0; bj < 2; ++bj) { f32x4 v0 = acc[ai][bj][m][0], v1 = acc[ai][bj][m][1];
; #pragma unroll
;                     for (int e = 0; e < 4; ++e) { const float a = fmaxf(v0[e], 0.f), b = fmaxf(v1[e], 0.f); v0[e] = a * a; v1[e] = b * b; }
;                     u32x4 w; w.x = pk2(v0[0], v0[1]); w.y = pk2(v0[2], v0[3]); w.z = pk2(v1[0], v1[1]); w.w = pk2(v1[2], v1[3]);
;                     const int kblk = u.pn * 4 + bj * 2 + (wc >> 1);
;                     *(GAS u32x4*)(O + ((size_t)kblk * MROWS + row) * 64 + 32 * (wc & 1) + 8 * fq) = w; } }
.LBB0_146:
	v_max_f32_e32 v122, v122, v122
	v_max_f32_e32 v123, v123, v123
	v_max_f32_e32 v122, 0, v122
	v_max_f32_e32 v123, 0, v123
	v_max_f32_e32 v126, v126, v126
	v_max_f32_e32 v127, v127, v127
	v_pk_mul_f32 v[148:149], v[122:123], v[122:123]
	v_max_f32_e32 v123, v124, v124
	v_lshl_add_u32 v142, s22, 8, v144
	s_lshl_b32 s15, s66, 2
	v_max_f32_e32 v126, 0, v126
	v_max_f32_e32 v127, 0, v127
	v_max_f32_e32 v122, v128, v128
	v_max_f32_e32 v124, 0, v123
	v_max_f32_e32 v123, v129, v129
	s_or_b32 s15, s15, s63
	v_ashrrev_i32_e32 v143, 31, v142
	v_pk_mul_f32 v[126:127], v[126:127], v[126:127]
	v_max_f32_e32 v122, 0, v122
	v_max_f32_e32 v123, 0, v123
	v_max_f32_e32 v125, v125, v125
	v_max_f32_e32 v125, 0, v125
	v_pk_mul_f32 v[128:129], v[122:123], v[122:123]
	v_cvt_pk_bf16_f32 v122, v126, v127
	v_mad_i64_i32 v[126:127], s[24:25], s15, v230, v[142:143]
	v_pk_mul_f32 v[150:151], v[124:125], v[124:125]
	v_lshlrev_b64 v[126:127], 7, v[126:127]
	v_max_f32_e32 v114, v114, v114
	v_max_f32_e32 v115, v115, v115
	v_cvt_pk_bf16_f32 v123, v128, v129
	v_cvt_pk_bf16_f32 v124, v148, v149
	v_cvt_pk_bf16_f32 v125, v150, v151
	v_lshl_add_u64 v[126:127], v[136:137], 0, v[126:127]
	v_max_f32_e32 v114, 0, v114
	v_max_f32_e32 v115, 0, v115
	v_mbcnt_lo_u32_b32 v176, -1, 0
	v_mbcnt_hi_u32_b32 v176, -1, v176
	v_and_b32_e32 v177, 3, v176
	v_lshrrev_b32_e32 v176, 2, v176
	v_lshl_add_u32 v176, v177, 4, v176
	v_lshlrev_b32_e32 v176, 2, v176
	ds_bpermute_b32 v160, v176, v122
	ds_bpermute_b32 v161, v176, v123
	ds_bpermute_b32 v162, v176, v124
	ds_bpermute_b32 v163, v176, v125
	ds_bpermute_b32 v164, v176, v126
	ds_bpermute_b32 v165, v176, v127
	v_max_f32_e32 v118, v118, v118
	v_max_f32_e32 v119, v119, v119
	v_pk_mul_f32 v[122:123], v[114:115], v[114:115]
	v_max_f32_e32 v115, v116, v116
	v_max_f32_e32 v118, 0, v118
	v_max_f32_e32 v119, 0, v119
	v_max_f32_e32 v114, v120, v120
	v_max_f32_e32 v116, 0, v115
	v_max_f32_e32 v115, v121, v121
	v_pk_mul_f32 v[118:119], v[118:119], v[118:119]
	v_max_f32_e32 v114, 0, v114
	v_max_f32_e32 v115, 0, v115
	v_max_f32_e32 v117, v117, v117
	s_or_b32 s17, s15, 2
	v_max_f32_e32 v117, 0, v117
	v_pk_mul_f32 v[120:121], v[114:115], v[114:115]
	v_cvt_pk_bf16_f32 v114, v118, v119
	v_mad_i64_i32 v[118:119], s[24:25], s17, v230, v[142:143]
	v_pk_mul_f32 v[124:125], v[116:117], v[116:117]
	v_lshlrev_b64 v[118:119], 7, v[118:119]
	v_max_f32_e32 v106, v106, v106
	v_max_f32_e32 v107, v107, v107
	v_cvt_pk_bf16_f32 v115, v120, v121
	v_cvt_pk_bf16_f32 v116, v122, v123
	v_cvt_pk_bf16_f32 v117, v124, v125
	v_lshl_add_u64 v[118:119], v[136:137], 0, v[118:119]
	v_max_f32_e32 v106, 0, v106
	v_max_f32_e32 v107, 0, v107
	s_waitcnt lgkmcnt(0)
	global_store_dwordx4 v[164:165], v[160:163], off
	ds_bpermute_b32 v168, v176, v114
	ds_bpermute_b32 v169, v176, v115
	ds_bpermute_b32 v170, v176, v116
	ds_bpermute_b32 v171, v176, v117
	ds_bpermute_b32 v172, v176, v118
	ds_bpermute_b32 v173, v176, v119
	v_max_f32_e32 v110, v110, v110
	v_max_f32_e32 v111, v111, v111
	v_pk_mul_f32 v[116:117], v[106:107], v[106:107]
	v_max_f32_e32 v107, v108, v108
	v_or_b32_e32 v114, 16, v142
	v_max_f32_e32 v110, 0, v110
	v_max_f32_e32 v111, 0, v111
	v_max_f32_e32 v106, v112, v112
	v_max_f32_e32 v108, 0, v107
	v_max_f32_e32 v107, v113, v113
	v_ashrrev_i32_e32 v115, 31, v114
	v_pk_mul_f32 v[110:111], v[110:111], v[110:111]
	v_max_f32_e32 v106, 0, v106
	v_max_f32_e32 v107, 0, v107
	v_max_f32_e32 v109, v109, v109
	v_max_f32_e32 v109, 0, v109
	v_pk_mul_f32 v[112:113], v[106:107], v[106:107]
	v_cvt_pk_bf16_f32 v106, v110, v111
	v_mad_i64_i32 v[110:111], s[24:25], s15, v230, v[114:115]
	v_pk_mul_f32 v[118:119], v[108:109], v[108:109]
	v_lshlrev_b64 v[110:111], 7, v[110:111]
	v_max_f32_e32 v98, v98, v98
	v_max_f32_e32 v99, v99, v99
	v_cvt_pk_bf16_f32 v107, v112, v113
	v_cvt_pk_bf16_f32 v108, v116, v117
	v_cvt_pk_bf16_f32 v109, v118, v119
	v_lshl_add_u64 v[110:111], v[136:137], 0, v[110:111]
	v_max_f32_e32 v98, 0, v98
	v_max_f32_e32 v99, 0, v99
	s_waitcnt lgkmcnt(0)
	global_store_dwordx4 v[172:173], v[168:171], off
	ds_bpermute_b32 v160, v176, v106
	ds_bpermute_b32 v161, v176, v107
	ds_bpermute_b32 v162, v176, v108
	ds_bpermute_b32 v163, v176, v109
	ds_bpermute_b32 v164, v176, v110
	ds_bpermute_b32 v165, v176, v111
	v_max_f32_e32 v102, v102, v102
	v_max_f32_e32 v103, v103, v103
	v_pk_mul_f32 v[106:107], v[98:99], v[98:99]
	v_max_f32_e32 v99, v100, v100
	v_max_f32_e32 v102, 0, v102
	v_max_f32_e32 v103, 0, v103
	v_max_f32_e32 v98, v104, v104
	v_max_f32_e32 v100, 0, v99
	v_max_f32_e32 v99, v105, v105
	v_pk_mul_f32 v[102:103], v[102:103], v[102:103]
	v_max_f32_e32 v98, 0, v98
	v_max_f32_e32 v99, 0, v99
	v_max_f32_e32 v101, v101, v101
	v_max_f32_e32 v101, 0, v101
	v_pk_mul_f32 v[104:105], v[98:99], v[98:99]
	v_cvt_pk_bf16_f32 v98, v102, v103
	v_mad_i64_i32 v[102:103], s[24:25], s17, v230, v[114:115]
	v_pk_mul_f32 v[108:109], v[100:101], v[100:101]
	v_lshlrev_b64 v[102:103], 7, v[102:103]
	v_max_f32_e32 v90, v90, v90
	v_max_f32_e32 v91, v91, v91
	v_cvt_pk_bf16_f32 v99, v104, v105
	v_cvt_pk_bf16_f32 v100, v106, v107
	v_cvt_pk_bf16_f32 v101, v108, v109
	v_lshl_add_u64 v[102:103], v[136:137], 0, v[102:103]
	v_max_f32_e32 v90, 0, v90
	v_max_f32_e32 v91, 0, v91
	s_waitcnt lgkmcnt(0)
; #define GAS __attribute__((address_space(1)))
; DI unsigned pk2(float lo, float hi) { f32x2 v = {lo, hi}; bf16x2_t b = __builtin_convertvector(v, bf16x2_t); return __builtin_bit_cast(unsigned, b); }
;     __device__ __forceinline__ void operator()(const f32x4 (&acc)[2][2][4][2], const Unit& u, int wr, int wc, int fr, int fq) const {
;         const int row0 = u.pm * BM + wr * 64 + fr;
; #pragma unroll
;         for (int ai = 0; ai < 2; ++ai)
; #pragma unroll
;             for (int m = 0; m < 4; ++m) { const int row = row0 + ai * HALF + m * 16;
; #pragma unroll
;                 for (int bj = 0; bj < 2; ++bj) { f32x4 v0 = acc[ai][bj][m][0], v1 = acc[ai][bj][m][1];
; #pragma unroll
;                     for (int e = 0; e < 4; ++e) { const float a = fmaxf(v0[e], 0.f), b = fmaxf(v1[e], 0.f); v0[e] = a * a; v1[e] = b * b; }
;                     u32x4 w; w.x = pk2(v0[0], v0[1]); w.y = pk2(v0[2], v0[3]); w.z = pk2(v1[0], v1[1]); w.w = pk2(v1[2], v1[3]);
;                     const int kblk = u.pn * 4 + bj * 2 + (wc >> 1);
;                     *(GAS u32x4*)(O + ((size_t)kblk * MROWS + row) * 64 + 32 * (wc & 1) + 8 * fq) = w; } }
	global_store_dwordx4 v[164:165], v[160:163], off
	ds_bpermute_b32 v168, v176, v98
	ds_bpermute_b32 v169, v176, v99
	ds_bpermute_b32 v170, v176, v100
	ds_bpermute_b32 v171, v176, v101
	ds_bpermute_b32 v172, v176, v102
	ds_bpermute_b32 v173, v176, v103
	v_max_f32_e32 v94, v94, v94
	v_max_f32_e32 v95, v95, v95
	v_pk_mul_f32 v[100:101], v[90:91], v[90:91]
	v_max_f32_e32 v91, v92, v92
	v_or_b32_e32 v98, 32, v142
	v_max_f32_e32 v94, 0, v94
	v_max_f32_e32 v95, 0, v95
	v_max_f32_e32 v90, v96, v96
	v_max_f32_e32 v92, 0, v91
	v_max_f32_e32 v91, v97, v97
	v_ashrrev_i32_e32 v99, 31, v98
	v_pk_mul_f32 v[94:95], v[94:95], v[94:95]
	v_max_f32_e32 v90, 0, v90
	v_max_f32_e32 v91, 0, v91
	v_max_f32_e32 v93, v93, v93
	v_max_f32_e32 v93, 0, v93
	v_pk_mul_f32 v[96:97], v[90:91], v[90:91]
	v_cvt_pk_bf16_f32 v90, v94, v95
	v_mad_i64_i32 v[94:95], s[24:25], s15, v230, v[98:99]
	v_pk_mul_f32 v[102:103], v[92:93], v[92:93]
	v_lshlrev_b64 v[94:95], 7, v[94:95]
	v_max_f32_e32 v82, v82, v82
	v_max_f32_e32 v83, v83, v83
	v_cvt_pk_bf16_f32 v91, v96, v97
	v_cvt_pk_bf16_f32 v92, v100, v101
	v_cvt_pk_bf16_f32 v93, v102, v103
	v_lshl_add_u64 v[94:95], v[136:137], 0, v[94:95]
	v_max_f32_e32 v82, 0, v82
	v_max_f32_e32 v83, 0, v83
	s_waitcnt lgkmcnt(0)
	global_store_dwordx4 v[172:173], v[168:171], off
	ds_bpermute_b32 v160, v176, v90
	ds_bpermute_b32 v161, v176, v91
	ds_bpermute_b32 v162, v176, v92
	ds_bpermute_b32 v163, v176, v93
	ds_bpermute_b32 v164, v176, v94
	ds_bpermute_b32 v165, v176, v95
	v_max_f32_e32 v86, v86, v86
	v_max_f32_e32 v87, v87, v87
	v_pk_mul_f32 v[90:91], v[82:83], v[82:83]
	v_max_f32_e32 v83, v84, v84
	v_max_f32_e32 v86, 0, v86
	v_max_f32_e32 v87, 0, v87
	v_max_f32_e32 v82, v88, v88
	v_max_f32_e32 v84, 0, v83
	v_max_f32_e32 v83, v89, v89
	v_pk_mul_f32 v[86:87], v[86:87], v[86:87]
	v_max_f32_e32 v82, 0, v82
	v_max_f32_e32 v83, 0, v83
	v_max_f32_e32 v85, v85, v85
	v_max_f32_e32 v85, 0, v85
	v_pk_mul_f32 v[88:89], v[82:83], v[82:83]
	v_cvt_pk_bf16_f32 v82, v86, v87
	v_mad_i64_i32 v[86:87], s[24:25], s17, v230, v[98:99]
	v_pk_mul_f32 v[92:93], v[84:85], v[84:85]
	v_lshlrev_b64 v[86:87], 7, v[86:87]
	v_max_f32_e32 v74, v74, v74
	v_max_f32_e32 v75, v75, v75
	v_cvt_pk_bf16_f32 v83, v88, v89
	v_cvt_pk_bf16_f32 v84, v90, v91
	v_cvt_pk_bf16_f32 v85, v92, v93
	v_lshl_add_u64 v[86:87], v[136:137], 0, v[86:87]
	v_max_f32_e32 v74, 0, v74
	v_max_f32_e32 v75, 0, v75
	s_waitcnt lgkmcnt(0)
	global_store_dwordx4 v[164:165], v[160:163], off
	ds_bpermute_b32 v168, v176, v82
	ds_bpermute_b32 v169, v176, v83
	ds_bpermute_b32 v170, v176, v84
	ds_bpermute_b32 v171, v176, v85
	ds_bpermute_b32 v172, v176, v86
	ds_bpermute_b32 v173, v176, v87
	v_max_f32_e32 v78, v78, v78
	v_max_f32_e32 v79, v79, v79
	v_pk_mul_f32 v[84:85], v[74:75], v[74:75]
	v_max_f32_e32 v75, v76, v76
	v_or_b32_e32 v82, 48, v142
	v_max_f32_e32 v78, 0, v78
	v_max_f32_e32 v79, 0, v79
	v_max_f32_e32 v74, v80, v80
	v_max_f32_e32 v76, 0, v75
	v_max_f32_e32 v75, v81, v81
	v_ashrrev_i32_e32 v83, 31, v82
	v_pk_mul_f32 v[78:79], v[78:79], v[78:79]
	v_max_f32_e32 v74, 0, v74
	v_max_f32_e32 v75, 0, v75
	v_max_f32_e32 v77, v77, v77
	v_max_f32_e32 v77, 0, v77
	v_pk_mul_f32 v[80:81], v[74:75], v[74:75]
	v_cvt_pk_bf16_f32 v74, v78, v79
	v_mad_i64_i32 v[78:79], s[24:25], s15, v230, v[82:83]
	v_pk_mul_f32 v[86:87], v[76:77], v[76:77]
	v_lshlrev_b64 v[78:79], 7, v[78:79]
	v_max_f32_e32 v66, v66, v66
	v_max_f32_e32 v67, v67, v67
	v_cvt_pk_bf16_f32 v75, v80, v81
	v_cvt_pk_bf16_f32 v76, v84, v85
	v_cvt_pk_bf16_f32 v77, v86, v87
	v_lshl_add_u64 v[78:79], v[136:137], 0, v[78:79]
	v_max_f32_e32 v66, 0, v66
	v_max_f32_e32 v67, 0, v67
	s_waitcnt lgkmcnt(0)
	global_store_dwordx4 v[172:173], v[168:171], off
	ds_bpermute_b32 v160, v176, v74
	ds_bpermute_b32 v161, v176, v75
	ds_bpermute_b32 v162, v176, v76
	ds_bpermute_b32 v163, v176, v77
	ds_bpermute_b32 v164, v176, v78
	ds_bpermute_b32 v165, v176, v79
	v_max_f32_e32 v70, v70, v70
	v_max_f32_e32 v71, v71, v71
	v_pk_mul_f32 v[74:75], v[66:67], v[66:67]
	v_max_f32_e32 v67, v68, v68
	v_max_f32_e32 v70, 0, v70
	v_max_f32_e32 v71, 0, v71
	v_max_f32_e32 v66, v72, v72
	v_max_f32_e32 v68, 0, v67
	v_max_f32_e32 v67, v73, v73
	v_pk_mul_f32 v[70:71], v[70:71], v[70:71]
	v_max_f32_e32 v66, 0, v66
	v_max_f32_e32 v67, 0, v67
	v_max_f32_e32 v69, v69, v69
	v_max_f32_e32 v69, 0, v69
	v_pk_mul_f32 v[72:73], v[66:67], v[66:67]
	v_cvt_pk_bf16_f32 v66, v70, v71
	v_mad_i64_i32 v[70:71], s[24:25], s17, v230, v[82:83]
	v_pk_mul_f32 v[76:77], v[68:69], v[68:69]
	v_lshlrev_b64 v[70:71], 7, v[70:71]
	v_max_f32_e32 v58, v58, v58
	v_max_f32_e32 v59, v59, v59
	v_cvt_pk_bf16_f32 v67, v72, v73
	v_cvt_pk_bf16_f32 v68, v74, v75
	v_cvt_pk_bf16_f32 v69, v76, v77
	v_lshl_add_u64 v[70:71], v[136:137], 0, v[70:71]
	v_max_f32_e32 v58, 0, v58
	v_max_f32_e32 v59, 0, v59
	s_waitcnt lgkmcnt(0)
	global_store_dwordx4 v[164:165], v[160:163], off
	ds_bpermute_b32 v168, v176, v66
	ds_bpermute_b32 v169, v176, v67
	ds_bpermute_b32 v170, v176, v68
	ds_bpermute_b32 v171, v176, v69
	ds_bpermute_b32 v172, v176, v70
	ds_bpermute_b32 v173, v176, v71
	v_max_f32_e32 v62, v62, v62
	v_max_f32_e32 v63, v63, v63
	v_pk_mul_f32 v[68:69], v[58:59], v[58:59]
	v_max_f32_e32 v59, v60, v60
	v_add_u32_e32 v66, 0x80, v142
	v_max_f32_e32 v62, 0, v62
	v_max_f32_e32 v63, 0, v63
	v_max_f32_e32 v58, v64, v64
	v_max_f32_e32 v60, 0, v59
	v_max_f32_e32 v59, v65, v65
	v_ashrrev_i32_e32 v67, 31, v66
	v_pk_mul_f32 v[62:63], v[62:63], v[62:63]
	v_max_f32_e32 v58, 0, v58
	v_max_f32_e32 v59, 0, v59
	v_max_f32_e32 v61, v61, v61
	v_max_f32_e32 v61, 0, v61
	v_pk_mul_f32 v[64:65], v[58:59], v[58:59]
	v_cvt_pk_bf16_f32 v58, v62, v63
	v_mad_i64_i32 v[62:63], s[24:25], s15, v230, v[66:67]
	v_pk_mul_f32 v[70:71], v[60:61], v[60:61]
	v_lshlrev_b64 v[62:63], 7, v[62:63]
	v_max_f32_e32 v50, v50, v50
	v_max_f32_e32 v51, v51, v51
	v_cvt_pk_bf16_f32 v59, v64, v65
	v_cvt_pk_bf16_f32 v60, v68, v69
	v_cvt_pk_bf16_f32 v61, v70, v71
	v_lshl_add_u64 v[62:63], v[136:137], 0, v[62:63]
	v_max_f32_e32 v50, 0, v50
	v_max_f32_e32 v51, 0, v51
	s_waitcnt lgkmcnt(0)
; #define GAS __attribute__((address_space(1)))
; DI unsigned pk2(float lo, float hi) { f32x2 v = {lo, hi}; bf16x2_t b = __builtin_convertvector(v, bf16x2_t); return __builtin_bit_cast(unsigned, b); }
;     __device__ __forceinline__ void operator()(const f32x4 (&acc)[2][2][4][2], const Unit& u, int wr, int wc, int fr, int fq) const {
;         const int row0 = u.pm * BM + wr * 64 + fr;
; #pragma unroll
;         for (int ai = 0; ai < 2; ++ai)
; #pragma unroll
;             for (int m = 0; m < 4; ++m) { const int row = row0 + ai * HALF + m * 16;
; #pragma unroll
;                 for (int bj = 0; bj < 2; ++bj) { f32x4 v0 = acc[ai][bj][m][0], v1 = acc[ai][bj][m][1];
; #pragma unroll
;                     for (int e = 0; e < 4; ++e) { const float a = fmaxf(v0[e], 0.f), b = fmaxf(v1[e], 0.f); v0[e] = a * a; v1[e] = b * b; }
;                     u32x4 w; w.x = pk2(v0[0], v0[1]); w.y = pk2(v0[2], v0[3]); w.z = pk2(v1[0], v1[1]); w.w = pk2(v1[2], v1[3]);
;                     const int kblk = u.pn * 4 + bj * 2 + (wc >> 1);
;                     *(GAS u32x4*)(O + ((size_t)kblk * MROWS + row) * 64 + 32 * (wc & 1) + 8 * fq) = w; } }
	global_store_dwordx4 v[172:173], v[168:171], off
	ds_bpermute_b32 v160, v176, v58
	ds_bpermute_b32 v161, v176, v59
	ds_bpermute_b32 v162, v176, v60
	ds_bpermute_b32 v163, v176, v61
	ds_bpermute_b32 v164, v176, v62
	ds_bpermute_b32 v165, v176, v63
	v_max_f32_e32 v54, v54, v54
	v_max_f32_e32 v55, v55, v55
	v_pk_mul_f32 v[58:59], v[50:51], v[50:51]
	v_max_f32_e32 v51, v52, v52
	v_max_f32_e32 v54, 0, v54
	v_max_f32_e32 v55, 0, v55
	v_max_f32_e32 v50, v56, v56
	v_max_f32_e32 v52, 0, v51
	v_max_f32_e32 v51, v57, v57
	v_pk_mul_f32 v[54:55], v[54:55], v[54:55]
	v_max_f32_e32 v50, 0, v50
	v_max_f32_e32 v51, 0, v51
	v_max_f32_e32 v53, v53, v53
	v_max_f32_e32 v53, 0, v53
	v_pk_mul_f32 v[56:57], v[50:51], v[50:51]
	v_cvt_pk_bf16_f32 v50, v54, v55
	v_mad_i64_i32 v[54:55], s[24:25], s17, v230, v[66:67]
	v_pk_mul_f32 v[60:61], v[52:53], v[52:53]
	v_lshlrev_b64 v[54:55], 7, v[54:55]
	v_max_f32_e32 v42, v42, v42
	v_max_f32_e32 v43, v43, v43
	v_cvt_pk_bf16_f32 v51, v56, v57
	v_cvt_pk_bf16_f32 v52, v58, v59
	v_cvt_pk_bf16_f32 v53, v60, v61
	v_lshl_add_u64 v[54:55], v[136:137], 0, v[54:55]
	v_max_f32_e32 v42, 0, v42
	v_max_f32_e32 v43, 0, v43
	s_waitcnt lgkmcnt(0)
	global_store_dwordx4 v[164:165], v[160:163], off
	ds_bpermute_b32 v168, v176, v50
	ds_bpermute_b32 v169, v176, v51
	ds_bpermute_b32 v170, v176, v52
	ds_bpermute_b32 v171, v176, v53
	ds_bpermute_b32 v172, v176, v54
	ds_bpermute_b32 v173, v176, v55
	v_max_f32_e32 v46, v46, v46
	v_max_f32_e32 v47, v47, v47
	v_pk_mul_f32 v[52:53], v[42:43], v[42:43]
	v_max_f32_e32 v43, v44, v44
	v_add_u32_e32 v50, 0x90, v142
	v_max_f32_e32 v46, 0, v46
	v_max_f32_e32 v47, 0, v47
	v_max_f32_e32 v42, v48, v48
	v_max_f32_e32 v44, 0, v43
	v_max_f32_e32 v43, v49, v49
	v_ashrrev_i32_e32 v51, 31, v50
	v_pk_mul_f32 v[46:47], v[46:47], v[46:47]
	v_max_f32_e32 v42, 0, v42
	v_max_f32_e32 v43, 0, v43
	v_max_f32_e32 v45, v45, v45
	v_max_f32_e32 v45, 0, v45
	v_pk_mul_f32 v[48:49], v[42:43], v[42:43]
	v_cvt_pk_bf16_f32 v42, v46, v47
	v_mad_i64_i32 v[46:47], s[24:25], s15, v230, v[50:51]
	v_pk_mul_f32 v[54:55], v[44:45], v[44:45]
	v_lshlrev_b64 v[46:47], 7, v[46:47]
	v_max_f32_e32 v34, v34, v34
	v_max_f32_e32 v35, v35, v35
	v_cvt_pk_bf16_f32 v43, v48, v49
	v_cvt_pk_bf16_f32 v44, v52, v53
	v_cvt_pk_bf16_f32 v45, v54, v55
	v_lshl_add_u64 v[46:47], v[136:137], 0, v[46:47]
	v_max_f32_e32 v34, 0, v34
	v_max_f32_e32 v35, 0, v35
	s_waitcnt lgkmcnt(0)
	global_store_dwordx4 v[172:173], v[168:171], off
	ds_bpermute_b32 v160, v176, v42
	ds_bpermute_b32 v161, v176, v43
	ds_bpermute_b32 v162, v176, v44
	ds_bpermute_b32 v163, v176, v45
	ds_bpermute_b32 v164, v176, v46
	ds_bpermute_b32 v165, v176, v47
	v_max_f32_e32 v38, v38, v38
	v_max_f32_e32 v39, v39, v39
	v_pk_mul_f32 v[42:43], v[34:35], v[34:35]
	v_max_f32_e32 v35, v36, v36
	v_max_f32_e32 v38, 0, v38
	v_max_f32_e32 v39, 0, v39
	v_max_f32_e32 v34, v40, v40
	v_max_f32_e32 v36, 0, v35
	v_max_f32_e32 v35, v41, v41
	v_pk_mul_f32 v[38:39], v[38:39], v[38:39]
	v_max_f32_e32 v34, 0, v34
	v_max_f32_e32 v35, 0, v35
	v_max_f32_e32 v37, v37, v37
	v_max_f32_e32 v37, 0, v37
	v_pk_mul_f32 v[40:41], v[34:35], v[34:35]
	v_cvt_pk_bf16_f32 v34, v38, v39
	v_mad_i64_i32 v[38:39], s[24:25], s17, v230, v[50:51]
	v_pk_mul_f32 v[44:45], v[36:37], v[36:37]
	v_lshlrev_b64 v[38:39], 7, v[38:39]
	v_max_f32_e32 v26, v26, v26
	v_max_f32_e32 v27, v27, v27
	v_cvt_pk_bf16_f32 v35, v40, v41
	v_cvt_pk_bf16_f32 v36, v42, v43
	v_cvt_pk_bf16_f32 v37, v44, v45
	v_lshl_add_u64 v[38:39], v[136:137], 0, v[38:39]
	v_max_f32_e32 v26, 0, v26
	v_max_f32_e32 v27, 0, v27
	s_waitcnt lgkmcnt(0)
	global_store_dwordx4 v[164:165], v[160:163], off
	ds_bpermute_b32 v168, v176, v34
	ds_bpermute_b32 v169, v176, v35
	ds_bpermute_b32 v170, v176, v36
	ds_bpermute_b32 v171, v176, v37
	ds_bpermute_b32 v172, v176, v38
	ds_bpermute_b32 v173, v176, v39
	v_max_f32_e32 v30, v30, v30
	v_max_f32_e32 v31, v31, v31
	v_pk_mul_f32 v[36:37], v[26:27], v[26:27]
	v_max_f32_e32 v27, v28, v28
	v_add_u32_e32 v34, 0xa0, v142
	v_max_f32_e32 v30, 0, v30
	v_max_f32_e32 v31, 0, v31
	v_max_f32_e32 v26, v32, v32
	v_max_f32_e32 v28, 0, v27
	v_max_f32_e32 v27, v33, v33
	v_ashrrev_i32_e32 v35, 31, v34
	v_pk_mul_f32 v[30:31], v[30:31], v[30:31]
	v_max_f32_e32 v26, 0, v26
	v_max_f32_e32 v27, 0, v27
	v_max_f32_e32 v29, v29, v29
	v_max_f32_e32 v29, 0, v29
	v_pk_mul_f32 v[32:33], v[26:27], v[26:27]
	v_cvt_pk_bf16_f32 v26, v30, v31
	v_mad_i64_i32 v[30:31], s[24:25], s15, v230, v[34:35]
	v_pk_mul_f32 v[38:39], v[28:29], v[28:29]
	v_lshlrev_b64 v[30:31], 7, v[30:31]
	v_max_f32_e32 v18, v18, v18
	v_max_f32_e32 v19, v19, v19
	v_cvt_pk_bf16_f32 v27, v32, v33
	v_cvt_pk_bf16_f32 v28, v36, v37
	v_cvt_pk_bf16_f32 v29, v38, v39
	v_lshl_add_u64 v[30:31], v[136:137], 0, v[30:31]
	v_max_f32_e32 v18, 0, v18
	v_max_f32_e32 v19, 0, v19
	s_waitcnt lgkmcnt(0)
; #define GAS __attribute__((address_space(1)))
; DI unsigned pk2(float lo, float hi) { f32x2 v = {lo, hi}; bf16x2_t b = __builtin_convertvector(v, bf16x2_t); return __builtin_bit_cast(unsigned, b); }
; #define PG8_BAR __builtin_amdgcn_s_barrier()
; template <class Epi, bool ALIGN_EPI>
; __device__ __forceinline__ void gemm_phase(LAS unsigned char* lds, const int tid, const Gemm g, const StaticOrder& S, const Epi& E) {
;     ...
;         if (!has_next) break;
; #pragma unroll
;         for (int a = 0; a < 2; ++a)
; #pragma unroll
;             for (int b = 0; b < 2; ++b)
; #pragma unroll
;                 for (int m = 0; m < 4; ++m)
; #pragma unroll
;                     for (int n = 0; n < 2; ++n) acc[a][b][m][n] = (f32x4){0.f, 0.f, 0.f, 0.f};
;         cur = nxt; cA = nA; cB = nB; ++ui;
;         if constexpr (ALIGN_EPI) { if (wr == 1) PG8_BAR; }
;     __device__ __forceinline__ void operator()(const f32x4 (&acc)[2][2][4][2], const Unit& u, int wr, int wc, int fr, int fq) const {
;         const int row0 = u.pm * BM + wr * 64 + fr;
; #pragma unroll
;         for (int ai = 0; ai < 2; ++ai)
; #pragma unroll
;             for (int m = 0; m < 4; ++m) { const int row = row0 + ai * HALF + m * 16;
; #pragma unroll
;                 for (int bj = 0; bj < 2; ++bj) { f32x4 v0 = acc[ai][bj][m][0], v1 = acc[ai][bj][m][1];
; #pragma unroll
;                     for (int e = 0; e < 4; ++e) { const float a = fmaxf(v0[e], 0.f), b = fmaxf(v1[e], 0.f); v0[e] = a * a; v1[e] = b * b; }
;                     u32x4 w; w.x = pk2(v0[0], v0[1]); w.y = pk2(v0[2], v0[3]); w.z = pk2(v1[0], v1[1]); w.w = pk2(v1[2], v1[3]);
;                     const int kblk = u.pn * 4 + bj * 2 + (wc >> 1);
;                     *(GAS u32x4*)(O + ((size_t)kblk * MROWS + row) * 64 + 32 * (wc & 1) + 8 * fq) = w; } }
	global_store_dwordx4 v[172:173], v[168:171], off
	ds_bpermute_b32 v160, v176, v26
	ds_bpermute_b32 v161, v176, v27
	ds_bpermute_b32 v162, v176, v28
	ds_bpermute_b32 v163, v176, v29
	ds_bpermute_b32 v164, v176, v30
	ds_bpermute_b32 v165, v176, v31
	v_max_f32_e32 v22, v22, v22
	v_max_f32_e32 v23, v23, v23
	v_pk_mul_f32 v[26:27], v[18:19], v[18:19]
	v_max_f32_e32 v19, v20, v20
	v_max_f32_e32 v22, 0, v22
	v_max_f32_e32 v23, 0, v23
	v_max_f32_e32 v18, v24, v24
	v_max_f32_e32 v20, 0, v19
	v_max_f32_e32 v19, v25, v25
	v_pk_mul_f32 v[22:23], v[22:23], v[22:23]
	v_max_f32_e32 v18, 0, v18
	v_max_f32_e32 v19, 0, v19
	v_max_f32_e32 v21, v21, v21
	v_max_f32_e32 v21, 0, v21
	v_pk_mul_f32 v[24:25], v[18:19], v[18:19]
	v_cvt_pk_bf16_f32 v18, v22, v23
	v_mad_i64_i32 v[22:23], s[24:25], s17, v230, v[34:35]
	v_pk_mul_f32 v[28:29], v[20:21], v[20:21]
	v_lshlrev_b64 v[22:23], 7, v[22:23]
	v_max_f32_e32 v10, v10, v10
	v_max_f32_e32 v11, v11, v11
	v_cvt_pk_bf16_f32 v19, v24, v25
	v_cvt_pk_bf16_f32 v20, v26, v27
	v_cvt_pk_bf16_f32 v21, v28, v29
	v_lshl_add_u64 v[22:23], v[136:137], 0, v[22:23]
	v_max_f32_e32 v10, 0, v10
	v_max_f32_e32 v11, 0, v11
	s_waitcnt lgkmcnt(0)
	global_store_dwordx4 v[164:165], v[160:163], off
	ds_bpermute_b32 v168, v176, v18
	ds_bpermute_b32 v169, v176, v19
	ds_bpermute_b32 v170, v176, v20
	ds_bpermute_b32 v171, v176, v21
	ds_bpermute_b32 v172, v176, v22
	ds_bpermute_b32 v173, v176, v23
	v_max_f32_e32 v14, v14, v14
	v_max_f32_e32 v15, v15, v15
	v_pk_mul_f32 v[20:21], v[10:11], v[10:11]
	v_max_f32_e32 v11, v12, v12
	v_add_u32_e32 v18, 0xb0, v142
	v_max_f32_e32 v14, 0, v14
	v_max_f32_e32 v15, 0, v15
	v_max_f32_e32 v10, v16, v16
	v_max_f32_e32 v12, 0, v11
	v_max_f32_e32 v11, v17, v17
	v_ashrrev_i32_e32 v19, 31, v18
	v_pk_mul_f32 v[14:15], v[14:15], v[14:15]
	v_max_f32_e32 v10, 0, v10
	v_max_f32_e32 v11, 0, v11
	v_max_f32_e32 v13, v13, v13
	v_max_f32_e32 v13, 0, v13
	v_pk_mul_f32 v[16:17], v[10:11], v[10:11]
	v_cvt_pk_bf16_f32 v10, v14, v15
	v_mad_i64_i32 v[14:15], s[24:25], s15, v230, v[18:19]
	v_pk_mul_f32 v[22:23], v[12:13], v[12:13]
	v_lshlrev_b64 v[14:15], 7, v[14:15]
	v_max_f32_e32 v2, v2, v2
	v_max_f32_e32 v3, v3, v3
	v_cvt_pk_bf16_f32 v11, v16, v17
	v_cvt_pk_bf16_f32 v12, v20, v21
	v_cvt_pk_bf16_f32 v13, v22, v23
	v_lshl_add_u64 v[14:15], v[136:137], 0, v[14:15]
	v_max_f32_e32 v2, 0, v2
	v_max_f32_e32 v3, 0, v3
	s_waitcnt lgkmcnt(0)
	global_store_dwordx4 v[172:173], v[168:171], off
	ds_bpermute_b32 v160, v176, v10
	ds_bpermute_b32 v161, v176, v11
	ds_bpermute_b32 v162, v176, v12
	ds_bpermute_b32 v163, v176, v13
	ds_bpermute_b32 v164, v176, v14
	ds_bpermute_b32 v165, v176, v15
	v_max_f32_e32 v6, v6, v6
	v_max_f32_e32 v7, v7, v7
	v_pk_mul_f32 v[10:11], v[2:3], v[2:3]
	v_max_f32_e32 v3, v4, v4
	v_max_f32_e32 v6, 0, v6
	v_max_f32_e32 v7, 0, v7
	v_max_f32_e32 v2, v8, v8
	v_max_f32_e32 v4, 0, v3
	v_max_f32_e32 v3, v9, v9
	v_pk_mul_f32 v[6:7], v[6:7], v[6:7]
	v_max_f32_e32 v2, 0, v2
	v_max_f32_e32 v3, 0, v3
	v_max_f32_e32 v5, v5, v5
	v_max_f32_e32 v5, 0, v5
	v_pk_mul_f32 v[8:9], v[2:3], v[2:3]
	v_cvt_pk_bf16_f32 v2, v6, v7
	v_mad_i64_i32 v[6:7], s[24:25], s17, v230, v[18:19]
	v_pk_mul_f32 v[12:13], v[4:5], v[4:5]
	v_lshlrev_b64 v[6:7], 7, v[6:7]
	v_cvt_pk_bf16_f32 v3, v8, v9
	v_cvt_pk_bf16_f32 v4, v10, v11
	v_cvt_pk_bf16_f32 v5, v12, v13
	v_lshl_add_u64 v[6:7], v[136:137], 0, v[6:7]
	s_andn2_b64 vcc, exec, s[0:1]
	s_mov_b64 s[0:1], -1
	s_mov_b32 s67, 0xf800000
	s_waitcnt lgkmcnt(0)
	global_store_dwordx4 v[164:165], v[160:163], off
	ds_bpermute_b32 v168, v176, v2
	ds_bpermute_b32 v169, v176, v3
	ds_bpermute_b32 v170, v176, v4
	ds_bpermute_b32 v171, v176, v5
	ds_bpermute_b32 v172, v176, v6
	ds_bpermute_b32 v173, v176, v7
	s_waitcnt lgkmcnt(0)
	global_store_dwordx4 v[172:173], v[168:171], off
	s_cbranch_vccnz .LBB0_139
	s_andn2_b64 vcc, exec, s[10:11]
	s_cbranch_vccnz .LBB0_138
	s_barrier
	s_branch .LBB0_138
